# DIFF unit prologue de-serialised: positions load issued with the Q loads (one memory round trip less per unit), on top of the kept version
# baseline (speedup 1.0000x reference)
; template <int MODE>
; __device__ __forceinline__ void flash_unit(ArgsP A, int l, int b, int h, int qb, unsigned char* lds) {
;     ...
;     } else if (MODE == 1) {
;         const float csc = 0.125f * LOG2E;
;         const bf16_t* qp = PROJ + (size_t)qrow * INWP + C_DQ + 128 * h + 64 * map + 8 * hh;
; #pragma unroll
;         for (int s = 0; s < NS; ++s) qf[s] = scale8(*(const u32x4*)(qp + 16 * s), csc);
;     } else {
;         const bf16_t* qp = PROJ + (size_t)qrow * INWP + C_RQ + 64 * h + 8 * hh;
; #pragma unroll
;         for (int s = 0; s < NS; ++s) qf[s] = __builtin_bit_cast(bf16x8, *(const u32x4*)(qp + 16 * s));
;     }
;     int posq = 0, qmin = 0; float bfar = 0.f;
;     if (MODE == 1) {
;         const int* pos = (const int*)A->in[2];
;         if (tid < 129) { int n = tid; int bucket;
;             if (n < 16) bucket = n; else { const float nf = (float)n; int lg = 16 + (int)(logf(nf / 16.f) / 2.0794415416798357f * 16.f); bucket = lg < 31 ? lg : 31; }
;             if (tid == 128) bucket = 31;
;             btab[tid] = A->in[3][bucket * 4 + h] * LOG2E; }
.Lprio_skip_diff:
	v_mov_b32_e32 v18, v238
	s_load_dwordx2 s[2:3], s[26:27], 0x148
	v_readfirstlane_b32 s24, v18
	s_ashr_i32 s17, s4, 4
	s_and_b32 s25, s4, 3
	s_ashr_i32 s14, s24, 6
	s_waitcnt lgkmcnt(0)
	s_add_u32 s10, s2, 0x18f90000
	v_writelane_b32 v255, s2, 15
	s_addc_u32 s11, s3, 0
	s_lshl_b32 s29, s14, 5
	s_lshl_b32 s9, s17, 7
	s_and_b32 s15, s29, 0x60
	s_sub_i32 s8, s15, s9
	v_and_b32_e32 v130, 31, v18
	v_writelane_b32 v255, s3, 16
	s_lshl_b32 s2, s4, 10
	s_addk_i32 s8, 0xf80
	s_and_b32 s16, s2, 0x3000
	v_or_b32_e32 v16, s8, v130
	v_add_u32_e32 v156, s16, v16
	v_mov_b64_e32 v[0:1], s[10:11]
	s_ashr_i32 s30, s24, 8
	v_mad_u64_u32 v[0:1], s[2:3], v156, s35, v[0:1]
	s_lshl_b32 s18, s25, 8
	s_lshl_b32 s2, s30, 6
	v_bfe_u32 v17, v18, 5, 1
	v_lshl_add_u64 v[0:1], v[0:1], 0, s[18:19]
	s_ashr_i32 s3, s2, 31
	v_lshl_add_u64 v[0:1], s[2:3], 1, v[0:1]
	v_lshlrev_b32_e32 v128, 4, v17
	v_mov_b32_e32 v129, v177
	v_lshl_add_u64 v[0:1], v[0:1], 0, v[128:129]
	s_mov_b64 s[2:3], 0x1580
	v_lshl_add_u64 v[2:3], v[0:1], 0, s[2:3]
	v_add_co_u32_e32 v0, vcc, 0x1000, v0
	s_movk_i32 s4, 0x81
	s_nop 0
	v_addc_co_u32_e32 v1, vcc, 0, v1, vcc
	global_load_dwordx4 v[12:15], v[0:1], off offset:1408
	global_load_dwordx4 v[8:11], v[2:3], off offset:32
	global_load_dwordx4 v[4:7], v[2:3], off offset:64
	s_nop 0
	global_load_dwordx4 v[0:3], v[2:3], off offset:96
	s_load_dwordx2 s[2:3], s[26:27], 0x10
	s_waitcnt lgkmcnt(0)
	v_mov_b32_e32 v212, v156
	v_mov_b32_e32 v213, 0
	v_lshl_add_u64 v[212:213], v[212:213], 2, s[2:3]
	global_load_dword v124, v[212:213], off
	v_cmp_gt_i32_e32 vcc, s4, v18
	s_and_saveexec_b64 s[4:5], vcc
	s_cbranch_execz .LBB0_806
	v_cmp_lt_i32_e32 vcc, 15, v18
	v_mov_b32_e32 v19, v18
	s_and_saveexec_b64 s[6:7], vcc
	s_cbranch_execz .LBB0_805
	v_cvt_f32_u32_e32 v19, v18
	s_mov_b32 s18, 0x800000
	v_mul_f32_e32 v19, 0x3d800000, v19
	v_cmp_gt_f32_e32 vcc, s18, v19
	s_mov_b32 s18, 0x3f317217
	s_nop 0
	v_cndmask_b32_e64 v20, 0, 32, vcc
	v_ldexp_f32 v19, v19, v20
	v_log_f32_e32 v19, v19
	v_mov_b32_e32 v20, 0x41b17218
	v_cndmask_b32_e32 v20, 0, v20, vcc
	v_mul_f32_e32 v21, 0x3f317217, v19
	v_fma_f32 v21, v19, s18, -v21
	v_fmac_f32_e32 v21, 0x3377d1cf, v19
	s_mov_b32 s18, 0x7f800000
	v_fmac_f32_e32 v21, 0x3f317217, v19
	v_cmp_lt_f32_e64 vcc, |v19|, s18
	s_mov_b32 s18, 0x40051592
	s_nop 0
	v_cndmask_b32_e32 v19, v19, v21, vcc
	v_sub_f32_e32 v19, v19, v20
	v_div_scale_f32 v20, s[20:21], s18, s18, v19
	v_rcp_f32_e32 v21, v20
	v_div_scale_f32 v22, vcc, v19, s18, v19
	v_fma_f32 v23, -v20, v21, 1.0
	v_fmac_f32_e32 v21, v23, v21
	v_mul_f32_e32 v23, v22, v21
	v_fma_f32 v24, -v20, v23, v22
	v_fmac_f32_e32 v23, v24, v21
	v_fma_f32 v20, -v20, v23, v22
	v_div_fmas_f32 v20, v20, v21, v23
	v_div_fixup_f32 v19, v20, s18, v19
	v_mul_f32_e32 v19, 0x41800000, v19
	v_cvt_i32_f32_e32 v19, v19
	v_min_i32_e32 v19, 15, v19
	v_add_u32_e32 v19, 16, v19

; template <int MODE>
; __device__ __forceinline__ void flash_unit(ArgsP A, int l, int b, int h, int qb, unsigned char* lds) {
;     ...
;     } else if (MODE == 1) {
;         const float csc = 0.125f * LOG2E;
;         const bf16_t* qp = PROJ + (size_t)qrow * INWP + C_DQ + 128 * h + 64 * map + 8 * hh;
; #pragma unroll
;         for (int s = 0; s < NS; ++s) qf[s] = scale8(*(const u32x4*)(qp + 16 * s), csc);
;     } else {
;         const bf16_t* qp = PROJ + (size_t)qrow * INWP + C_RQ + 64 * h + 8 * hh;
; #pragma unroll
;         for (int s = 0; s < NS; ++s) qf[s] = __builtin_bit_cast(bf16x8, *(const u32x4*)(qp + 16 * s));
;     }
;     int posq = 0, qmin = 0; float bfar = 0.f;
;     if (MODE == 1) {
;         const int* pos = (const int*)A->in[2];
;         if (tid < 129) { int n = tid; int bucket;
;             if (n < 16) bucket = n; else { const float nf = (float)n; int lg = 16 + (int)(logf(nf / 16.f) / 2.0794415416798357f * 16.f); bucket = lg < 31 ? lg : 31; }
;             if (tid == 128) bucket = 31;
;             btab[tid] = A->in[3][bucket * 4 + h] * LOG2E; }
;         posq = pos[qrow];
;         int mn = posq;
; #pragma unroll
;         for (int o = 1; o < 64; o <<= 1) { const int other = __shfl_xor(mn, o); mn = other < mn ? other : mn; }
;         qmin = mn;
;     }
.LBB0_806:
	s_or_b64 exec, exec, s[4:5]
	s_waitcnt vmcnt(4)
	v_lshlrev_b32_e32 v20, 16, v12
	v_and_b32_e32 v21, 0xffff0000, v12
	s_mov_b32 s6, 0x3e38aa3b
	v_lshlrev_b32_e32 v12, 16, v13
	v_and_b32_e32 v13, 0xffff0000, v13
	v_pk_mul_f32 v[12:13], v[12:13], s[6:7] op_sel_hi:[1,0]
	v_mov_b32_e32 v157, v177
	v_cvt_pk_bf16_f32 v97, v12, v13
	v_lshlrev_b32_e32 v12, 16, v14
	v_and_b32_e32 v13, 0xffff0000, v14
	v_pk_mul_f32 v[12:13], v[12:13], s[6:7] op_sel_hi:[1,0]
	v_pk_mul_f32 v[20:21], v[20:21], s[6:7] op_sel_hi:[1,0]
	v_cvt_pk_bf16_f32 v98, v12, v13
	v_lshlrev_b32_e32 v12, 16, v15
	v_and_b32_e32 v13, 0xffff0000, v15
	v_pk_mul_f32 v[12:13], v[12:13], s[6:7] op_sel_hi:[1,0]
	v_and_b32_e32 v112, 63, v18
	v_cvt_pk_bf16_f32 v99, v12, v13
	s_waitcnt vmcnt(3)
	v_lshlrev_b32_e32 v12, 16, v8
	v_and_b32_e32 v13, 0xffff0000, v8
	v_lshlrev_b32_e32 v8, 16, v9
	v_and_b32_e32 v9, 0xffff0000, v9
	v_pk_mul_f32 v[8:9], v[8:9], s[6:7] op_sel_hi:[1,0]
	v_pk_mul_f32 v[12:13], v[12:13], s[6:7] op_sel_hi:[1,0]
	v_cvt_pk_bf16_f32 v101, v8, v9
	v_lshlrev_b32_e32 v8, 16, v10
	v_and_b32_e32 v9, 0xffff0000, v10
	v_pk_mul_f32 v[8:9], v[8:9], s[6:7] op_sel_hi:[1,0]
	v_cvt_pk_bf16_f32 v96, v20, v21
	v_cvt_pk_bf16_f32 v102, v8, v9
	v_lshlrev_b32_e32 v8, 16, v11
	v_and_b32_e32 v9, 0xffff0000, v11
	v_pk_mul_f32 v[8:9], v[8:9], s[6:7] op_sel_hi:[1,0]
	v_cvt_pk_bf16_f32 v100, v12, v13
	v_cvt_pk_bf16_f32 v103, v8, v9
	s_waitcnt vmcnt(2)
	v_lshlrev_b32_e32 v8, 16, v4
	v_and_b32_e32 v9, 0xffff0000, v4
	v_lshlrev_b32_e32 v4, 16, v5
	v_and_b32_e32 v5, 0xffff0000, v5
	v_pk_mul_f32 v[4:5], v[4:5], s[6:7] op_sel_hi:[1,0]
	v_pk_mul_f32 v[8:9], v[8:9], s[6:7] op_sel_hi:[1,0]
	v_cvt_pk_bf16_f32 v105, v4, v5
	v_lshlrev_b32_e32 v4, 16, v6
	v_and_b32_e32 v5, 0xffff0000, v6
	v_pk_mul_f32 v[4:5], v[4:5], s[6:7] op_sel_hi:[1,0]
	v_cvt_pk_bf16_f32 v104, v8, v9
	v_cvt_pk_bf16_f32 v106, v4, v5
	v_lshlrev_b32_e32 v4, 16, v7
	v_and_b32_e32 v5, 0xffff0000, v7
	v_pk_mul_f32 v[4:5], v[4:5], s[6:7] op_sel_hi:[1,0]
	s_and_b32 s5, s24, 0xffffffc0
	v_cvt_pk_bf16_f32 v107, v4, v5
	s_waitcnt vmcnt(1)
	v_lshlrev_b32_e32 v4, 16, v0
	v_and_b32_e32 v5, 0xffff0000, v0
	v_lshlrev_b32_e32 v0, 16, v1
	v_and_b32_e32 v1, 0xffff0000, v1
	v_pk_mul_f32 v[0:1], v[0:1], s[6:7] op_sel_hi:[1,0]
	v_pk_mul_f32 v[4:5], v[4:5], s[6:7] op_sel_hi:[1,0]
	v_cvt_pk_bf16_f32 v109, v0, v1
	v_lshlrev_b32_e32 v0, 16, v2
	v_and_b32_e32 v1, 0xffff0000, v2
	v_pk_mul_f32 v[0:1], v[0:1], s[6:7] op_sel_hi:[1,0]
	v_xor_b32_e32 v2, 2, v179
	v_cvt_pk_bf16_f32 v110, v0, v1
	v_lshlrev_b32_e32 v0, 16, v3
	v_and_b32_e32 v1, 0xffff0000, v3
	v_pk_mul_f32 v[0:1], v[0:1], s[6:7] op_sel_hi:[1,0]
	v_cvt_pk_bf16_f32 v108, v4, v5
	v_cvt_pk_bf16_f32 v111, v0, v1
	s_waitcnt lgkmcnt(0)
	v_and_b32_e32 v0, 64, v179
	v_add_u32_e32 v0, 64, v0
	v_xor_b32_e32 v1, 1, v179
	v_cmp_lt_i32_e32 vcc, v1, v0
	v_or_b32_e32 v4, s5, v112
	s_nop 0
	v_cndmask_b32_e32 v1, v179, v1, vcc
	v_lshlrev_b32_e32 v1, 2, v1
	v_cmp_lt_i32_e32 vcc, v2, v0
	s_add_i32 s5, s14, 8
	v_lshl_or_b32 v5, s5, 6, v112
	v_cndmask_b32_e32 v2, v179, v2, vcc
	v_lshlrev_b32_e32 v2, 2, v2
	s_lshl_b32 s26, s5, 10
	s_ashr_i32 s6, s24, 4
	s_lshl_b32 s5, s5, 2
	s_lshl_b32 s4, s25, 7
	s_lshl_b32 s31, s14, 10
	s_and_b32 s25, s6, -8
	s_movk_i32 s6, 0x60
	s_and_b32 s34, s5, -8
	s_lshl_b32 s5, s16, 2
	s_add_u32 s36, s2, s5
	s_addc_u32 s37, s3, 0
	s_lshl_b32 s18, s4, 1
	s_cmp_lg_u32 16, -1
	s_mov_b64 s[20:21], 0x1980
	s_cselect_b32 s4, 16, 0
	s_mov_b64 s[22:23], 0x1d80
	s_add_i32 s5, s4, 0x10000
	v_mov_b32_e32 v119, v177
	v_mov_b32_e32 v113, v177
	s_waitcnt vmcnt(0)
	ds_bpermute_b32 v1, v1, v124
	s_waitcnt lgkmcnt(0)
	v_min_i32_e32 v1, v1, v124
	ds_bpermute_b32 v2, v2, v1
	s_waitcnt lgkmcnt(0)
	v_min_i32_e32 v1, v2, v1
	v_xor_b32_e32 v2, 4, v179
	v_cmp_lt_i32_e32 vcc, v2, v0
	s_nop 1
	v_cndmask_b32_e32 v2, v179, v2, vcc
	v_lshlrev_b32_e32 v2, 2, v2
	ds_bpermute_b32 v2, v2, v1
	s_waitcnt lgkmcnt(0)
	v_min_i32_e32 v1, v2, v1
	v_xor_b32_e32 v2, 8, v179
	v_cmp_lt_i32_e32 vcc, v2, v0
	s_nop 1
	v_cndmask_b32_e32 v2, v179, v2, vcc
	v_lshlrev_b32_e32 v2, 2, v2
	ds_bpermute_b32 v2, v2, v1
	s_waitcnt lgkmcnt(0)
	v_min_i32_e32 v1, v2, v1
	v_xor_b32_e32 v2, 16, v179
	v_cmp_lt_i32_e32 vcc, v2, v0
	s_nop 1
	v_cndmask_b32_e32 v2, v179, v2, vcc
	v_lshlrev_b32_e32 v2, 2, v2
	ds_bpermute_b32 v2, v2, v1
	s_waitcnt lgkmcnt(0)
	v_min_i32_e32 v1, v2, v1
	v_xor_b32_e32 v2, 32, v179
	v_cmp_lt_i32_e32 vcc, v2, v0
	s_nop 1
	v_cndmask_b32_e32 v0, v179, v2, vcc
	v_lshlrev_b32_e32 v174, 2, v0
	ds_bpermute_b32 v0, v174, v1
	s_waitcnt lgkmcnt(0)
	v_min_i32_e32 v125, v0, v1
	v_mov_b32_e32 v0, v177
	v_lshlrev_b32_e32 v1, 3, v112
	v_ashrrev_i32_e32 v0, 31, v4
	v_lshrrev_b32_e32 v0, 28, v0
	v_add_u32_e32 v0, v4, v0
	v_ashrrev_i32_e32 v2, 4, v0
	v_and_b32_e32 v0, 0x1ffffff0, v0
	v_sub_u32_e32 v0, v4, v0
	v_bitop3_b32 v0, v2, v0, 15 bitop3:0x6c
	v_lshlrev_b32_e32 v114, 3, v0
	v_ashrrev_i32_e32 v0, 31, v5
	v_lshrrev_b32_e32 v0, 28, v0
	v_add_u32_e32 v0, v5, v0
	v_ashrrev_i32_e32 v3, 4, v0
	v_and_b32_e32 v0, 0x1ffffff0, v0
	v_and_b32_e32 v1, 24, v1
	v_sub_u32_e32 v0, v5, v0
	v_and_or_b32 v12, v4, s6, v1
	v_and_or_b32 v13, v5, s6, v1
	v_add_u32_e32 v126, s16, v2
	v_mov_b64_e32 v[4:5], s[10:11]
	v_ashrrev_i32_e32 v115, 31, v114
	v_mad_i64_i32 v[6:7], s[2:3], v126, s35, v[4:5]
	v_lshl_add_u64 v[6:7], v[6:7], 0, s[18:19]
	v_lshlrev_b64 v[8:9], 1, v[114:115]
	v_bitop3_b32 v0, v3, v0, 15 bitop3:0x6c
	v_lshl_add_u64 v[6:7], v[6:7], 0, v[8:9]
	v_lshlrev_b32_e32 v116, 3, v0
	v_lshl_add_u64 v[6:7], v[6:7], 0, s[20:21]
	s_add_i32 s2, s31, s4
	v_add_u32_e32 v127, s16, v3
	s_barrier
; template <int MODE>
; __device__ __forceinline__ void flash_unit(ArgsP A, int l, int b, int h, int qb, unsigned char* lds) {
;     ...
;     auto dma_tile = [&](int t) {
;         const int kr0 = rowbase + 64 * t;
;         const int slot = t % NBUF; const unsigned kb_ = lds0 + slot * KBYTES, vb_ = lds0 + NBUF * KBYTES + slot * VBYTES;
; #pragma unroll
;         for (int i = 0; i < NKI; ++i) { const int piece = wave + 8 * i, p = 64 * piece + lane, key = p / KCH, cs = p % KCH;
;             const int ch = cs ^ (MODE == 1 ? (key & 15) : ((key >> 1) & 7)); const bf16_t* src;
;             if (MODE == 0) src = (ch < 16) ? KVM + (size_t)(kr0 + key) * 1024 + 256 * h + 8 * ch : PROJ + (size_t)(kr0 + key) * INWP + C_KR + 8 * (ch - 16);
;             else if (MODE == 1) src = PROJ + (size_t)(kr0 + key) * INWP + C_DK + 128 * h + 8 * ch;
;             else src = PROJ + (size_t)(kr0 + key) * INWP + C_RK + 64 * h + 8 * ch;
;             glds16(src, (unsigned)__builtin_amdgcn_readfirstlane(kb_ + piece * 1024)); }
; #pragma unroll
;         for (int i = 0; i < 2; ++i) { const int piece = wave + 8 * i, p = 64 * piece + lane, st = p >> 5, key = 8 * (st >> 2) + ((p & 31) >> 2), col = 32 * (st & 3) + 8 * (p & 3); const bf16_t* src;
;             if (MODE == 0) src = KVM + (size_t)(kr0 + key) * 1024 + 256 * h + 128 + col;
;             else if (MODE == 1) src = PROJ + (size_t)(kr0 + key) * INWP + C_DV + 128 * h + col;
;             else src = PROJ + (size_t)(kr0 + key) * INWP + C_RV + 128 * h + col;
;             glds16(src, (unsigned)__builtin_amdgcn_readfirstlane(vb_ + piece * 1024)); }
;         if (MODE == 1) glds4((const int*)A->in[2] + rowbase + 64 * t + lane, (unsigned)__builtin_amdgcn_readfirstlane(lds0 + OFF_EXTRA + slot * 256));
;     };
;     f32x16 oacc[4];
; #pragma unroll
;     for (int c = 0; c < 4; ++c)
; #pragma unroll
;         for (int i = 0; i < 16; ++i) oacc[c][i] = 0.f;
;     float m_run = -INFINITY, l_run = 0.f;
; #pragma unroll
;     for (int s_ = 0; s_ < NS; ++s_) asm volatile("" : "+v"(qf[s_]));
;     asm volatile("" : "+v"(posq), "+v"(qmin), "+v"(lg2));
;     __syncthreads();
; #pragma unroll
;     for (int i = 0; i < NBUF - 1; ++i) if (i < ntile) dma_tile(i);
	v_ashrrev_i32_e32 v117, 31, v116
	s_mov_b32 s3, m0
	s_mov_b32 m0, s2
	s_nop 0
	global_load_lds_dwordx4 v[6:7], off
	s_mov_b32 m0, s3
	v_lshlrev_b64 v[10:11], 1, v[116:117]
	v_mad_i64_i32 v[6:7], s[2:3], v127, s35, v[4:5]
	v_lshl_add_u64 v[6:7], v[6:7], 0, s[18:19]
	v_bfe_u32 v0, v18, 2, 3
	v_lshl_add_u64 v[6:7], v[6:7], 0, v[10:11]
	v_lshl_add_u64 v[6:7], v[6:7], 0, s[20:21]
	v_or_b32_e32 v14, s16, v0
	s_add_i32 s2, s26, s4
	s_mov_b32 s3, m0
	s_mov_b32 m0, s2
	s_nop 0
	global_load_lds_dwordx4 v[6:7], off
	s_mov_b32 m0, s3
	v_add_u32_e32 v6, s25, v14
	v_mad_i64_i32 v[6:7], s[2:3], v6, s35, v[4:5]
	v_lshl_add_u64 v[6:7], v[6:7], 0, s[18:19]
	v_lshlrev_b32_e32 v176, 1, v12
	v_lshl_add_u64 v[6:7], v[6:7], 0, v[176:177]
	v_lshl_add_u64 v[6:7], v[6:7], 0, s[22:23]
	s_add_i32 s2, s31, s5
	s_mov_b32 s3, m0
	s_mov_b32 m0, s2
	s_nop 0
	global_load_lds_dwordx4 v[6:7], off
	s_mov_b32 m0, s3
	v_add_u32_e32 v6, s34, v14
	v_mad_i64_i32 v[6:7], s[2:3], v6, s35, v[4:5]
	v_lshl_add_u64 v[6:7], v[6:7], 0, s[18:19]
	v_lshlrev_b32_e32 v118, 1, v13
	v_lshl_add_u64 v[6:7], v[6:7], 0, v[118:119]
	v_lshl_add_u64 v[6:7], v[6:7], 0, s[22:23]
	s_add_i32 s2, s26, s5
	s_or_b32 s5, s16, 64
	s_mov_b32 s3, m0
	s_mov_b32 m0, s2
	s_nop 0
	global_load_lds_dwordx4 v[6:7], off
	s_mov_b32 m0, s3
	v_lshlrev_b32_e32 v6, 2, v112
	v_mov_b32_e32 v7, v177
	s_add_i32 s2, s4, 0x20000
	v_add_u32_e32 v12, s5, v2
	v_lshl_add_u64 v[6:7], s[36:37], 0, v[6:7]
	s_mov_b32 s3, m0
	s_mov_b32 m0, s2
	s_nop 0
	global_load_lds_dword v[6:7], off
	s_mov_b32 m0, s3
	s_add_i32 s6, s4, 0x4000
	v_mad_i64_i32 v[12:13], s[2:3], v12, s35, v[4:5]
	v_lshl_add_u64 v[12:13], v[12:13], 0, s[18:19]
	v_lshl_add_u64 v[8:9], v[12:13], 0, v[8:9]
	v_lshl_add_u64 v[8:9], v[8:9], 0, s[20:21]
	s_add_i32 s2, s31, s6
	s_mov_b32 s3, m0
	s_mov_b32 m0, s2
	s_nop 0
	global_load_lds_dwordx4 v[8:9], off
	s_mov_b32 m0, s3
	v_add_u32_e32 v8, s5, v3
	v_mad_i64_i32 v[8:9], s[2:3], v8, s35, v[4:5]
	v_lshl_add_u64 v[8:9], v[8:9], 0, s[18:19]
	v_lshl_add_u64 v[8:9], v[8:9], 0, v[10:11]
	v_lshl_add_u64 v[8:9], v[8:9], 0, s[20:21]
	v_or_b32_e32 v10, s5, v0
	s_add_i32 s2, s26, s6
	s_mov_b32 s3, m0
	s_mov_b32 m0, s2
	s_nop 0
	global_load_lds_dwordx4 v[8:9], off
	s_mov_b32 m0, s3
	v_add_u32_e32 v8, s25, v10
	v_mad_i64_i32 v[8:9], s[2:3], v8, s35, v[4:5]
	v_lshl_add_u64 v[8:9], v[8:9], 0, s[18:19]
	v_lshl_add_u64 v[8:9], v[8:9], 0, v[176:177]
	v_lshl_add_u64 v[8:9], v[8:9], 0, s[22:23]
	s_add_i32 s5, s4, 0x14000
	s_add_i32 s2, s31, s5
	s_mov_b32 s3, m0
	s_mov_b32 m0, s2
	s_nop 0
	global_load_lds_dwordx4 v[8:9], off
	s_mov_b32 m0, s3
	v_add_u32_e32 v8, s34, v10
	v_mad_i64_i32 v[4:5], s[2:3], v8, s35, v[4:5]
	v_lshl_add_u64 v[4:5], v[4:5], 0, s[18:19]
	v_lshl_add_u64 v[4:5], v[4:5], 0, v[118:119]
	v_lshl_add_u64 v[4:5], v[4:5], 0, s[22:23]
	s_add_i32 s2, s26, s5
	s_mov_b32 s3, m0
	s_mov_b32 m0, s2
	s_nop 0
	global_load_lds_dwordx4 v[4:5], off
	s_mov_b32 m0, s3
	s_mov_b64 s[2:3], 0x100
	v_lshl_add_u64 v[4:5], v[6:7], 0, s[2:3]
	s_add_i32 s4, s4, 0x20100
	s_mov_b32 s2, m0
	s_mov_b32 m0, s4
	s_nop 0
	global_load_lds_dword v[4:5], off
	s_mov_b32 m0, s2
	s_cmp_eq_u32 s17, 31
	s_cbranch_scc1 .LBB0_808
	s_or_b32 s4, s16, 0x80
	v_add_u32_e32 v2, s4, v2
	v_mov_b64_e32 v[4:5], s[10:11]
	s_cmp_lg_u32 16, -1
	v_mad_i64_i32 v[6:7], s[2:3], v2, s35, v[4:5]
	s_cselect_b32 s5, 16, 0
	v_lshl_add_u64 v[6:7], v[6:7], 0, s[18:19]
	s_add_i32 s6, s5, 0x8000
	v_lshl_add_u64 v[6:7], v[114:115], 1, v[6:7]
	s_add_i32 s2, s31, s6
	v_add_u32_e32 v2, s4, v3
	v_lshl_add_u64 v[6:7], v[6:7], 0, s[20:21]
	s_mov_b32 s3, m0
	s_mov_b32 m0, s2
	s_nop 0
	global_load_lds_dwordx4 v[6:7], off
	s_mov_b32 m0, s3
	v_or_b32_e32 v6, s4, v0
	v_mad_i64_i32 v[2:3], s[2:3], v2, s35, v[4:5]
	v_lshl_add_u64 v[2:3], v[2:3], 0, s[18:19]
	v_lshl_add_u64 v[2:3], v[116:117], 1, v[2:3]
	v_lshl_add_u64 v[2:3], v[2:3], 0, s[20:21]
	s_add_i32 s2, s26, s6
	s_mov_b32 s3, m0
	s_mov_b32 m0, s2
	s_nop 0
	global_load_lds_dwordx4 v[2:3], off
	s_mov_b32 m0, s3
	v_add_u32_e32 v2, s25, v6
	v_mad_i64_i32 v[2:3], s[2:3], v2, s35, v[4:5]
	v_lshl_add_u64 v[2:3], v[2:3], 0, s[18:19]
	v_lshl_add_u64 v[2:3], v[2:3], 0, v[176:177]
	s_mov_b64 s[6:7], 0x1d80
	v_lshl_add_u64 v[2:3], v[2:3], 0, s[6:7]
	s_add_i32 s4, s5, 0x18000
	s_add_i32 s2, s31, s4
	s_mov_b32 s3, m0
	s_mov_b32 m0, s2
	s_nop 0
	global_load_lds_dwordx4 v[2:3], off
	s_mov_b32 m0, s3
	v_add_u32_e32 v2, s34, v6
	v_mad_i64_i32 v[2:3], s[2:3], v2, s35, v[4:5]
	v_lshl_add_u64 v[2:3], v[2:3], 0, s[18:19]
	v_lshl_add_u64 v[2:3], v[2:3], 0, v[118:119]
	v_lshl_add_u64 v[2:3], v[2:3], 0, s[6:7]
	s_add_i32 s2, s26, s4
	s_mov_b32 s3, m0
	s_mov_b32 m0, s2
	s_nop 0
	global_load_lds_dwordx4 v[2:3], off
	s_mov_b32 m0, s3
	v_lshl_add_u64 v[2:3], v[112:113], 2, s[36:37]
	s_mov_b64 s[2:3], 0x200
	v_lshl_add_u64 v[2:3], v[2:3], 0, s[2:3]
	s_add_i32 s5, s5, 0x20200
	s_mov_b32 s2, m0
	s_mov_b32 m0, s5
	s_nop 0
	global_load_lds_dword v[2:3], off
	s_mov_b32 m0, s2
